# hand-scheduled SwiGLU epilogue + GU accumulators cleared once per tile instead of twice + scalar phase header
# speedup vs baseline: 1.0223x; 1.0028x over previous
; template <class Epi, bool ALIGN_EPI>
; __device__ __forceinline__ void gemm_phase(LAS unsigned char* lds, const Gemm g, const StaticOrder& S, const Epi& E, const int tid) {
;     ...
;     f32x4 acc[2][2][4][2];
; #pragma unroll
;     for (int a = 0; a < 2; ++a)
; #pragma unroll
;         for (int b = 0; b < 2; ++b)
; #pragma unroll
;             for (int m = 0; m < 4; ++m)
; #pragma unroll
;                 for (int n = 0; n < 2; ++n) acc[a][b][m][n] = (f32x4){0.f, 0.f, 0.f, 0.f};
;     ...
;         for (int a = 0; a < 2; ++a)
; #pragma unroll
;             for (int b = 0; b < 2; ++b)
; #pragma unroll
;                 for (int m = 0; m < 4; ++m)
; #pragma unroll
;                     for (int n = 0; n < 2; ++n) acc[a][b][m][n] = (f32x4){0.f, 0.f, 0.f, 0.f};
.LBB0_306:
	s_andn2_b64 vcc, exec, s[36:37]
	s_cbranch_vccnz .LBB0_309
	v_mov_b32_e32 v0, 0
	v_lshl_add_u64 v[142:143], v[142:143], 0, s[92:93]
	v_lshl_add_u64 v[144:145], v[144:145], 0, s[80:81]
	s_mov_b32 s10, 0
	v_mov_b32_e32 v1, v0
	v_mov_b32_e32 v2, v0
	v_mov_b32_e32 v3, v0
	v_mov_b32_e32 v12, v0
	v_mov_b32_e32 v13, v0
	v_mov_b32_e32 v14, v0
	v_mov_b32_e32 v15, v0
	v_mov_b32_e32 v20, v0
	v_mov_b32_e32 v21, v0
	v_mov_b32_e32 v22, v0
	v_mov_b32_e32 v23, v0
	v_mov_b32_e32 v28, v0
	v_mov_b32_e32 v29, v0
	v_mov_b32_e32 v30, v0
	v_mov_b32_e32 v31, v0
	v_mov_b32_e32 v36, v0
	v_mov_b32_e32 v37, v0
	v_mov_b32_e32 v38, v0
	v_mov_b32_e32 v39, v0
	v_mov_b32_e32 v44, v0
	v_mov_b32_e32 v45, v0
	v_mov_b32_e32 v46, v0
	v_mov_b32_e32 v47, v0
	v_mov_b32_e32 v52, v0
	v_mov_b32_e32 v53, v0
	v_mov_b32_e32 v54, v0
	v_mov_b32_e32 v55, v0
	v_mov_b32_e32 v60, v0
	v_mov_b32_e32 v61, v0
	v_mov_b32_e32 v62, v0
	v_mov_b32_e32 v63, v0
	v_mov_b32_e32 v4, v0
	v_mov_b32_e32 v5, v0
	v_mov_b32_e32 v6, v0
	v_mov_b32_e32 v7, v0
	v_mov_b32_e32 v8, v0
	v_mov_b32_e32 v9, v0
	v_mov_b32_e32 v10, v0
	v_mov_b32_e32 v11, v0
	v_mov_b32_e32 v16, v0
	v_mov_b32_e32 v17, v0
	v_mov_b32_e32 v18, v0
	v_mov_b32_e32 v19, v0
	v_mov_b32_e32 v24, v0
	v_mov_b32_e32 v25, v0
	v_mov_b32_e32 v26, v0
	v_mov_b32_e32 v27, v0
	v_mov_b32_e32 v32, v0
	v_mov_b32_e32 v33, v0
	v_mov_b32_e32 v34, v0
	v_mov_b32_e32 v35, v0
	v_mov_b32_e32 v40, v0
	v_mov_b32_e32 v41, v0
	v_mov_b32_e32 v42, v0
	v_mov_b32_e32 v43, v0
	v_mov_b32_e32 v48, v0
	v_mov_b32_e32 v49, v0
	v_mov_b32_e32 v50, v0
	v_mov_b32_e32 v51, v0
	v_mov_b32_e32 v56, v0
	v_mov_b32_e32 v57, v0
	v_mov_b32_e32 v58, v0
	v_mov_b32_e32 v59, v0
	v_mov_b32_e32 v68, v0
	v_mov_b32_e32 v69, v0
	v_mov_b32_e32 v70, v0
	v_mov_b32_e32 v71, v0
	v_mov_b32_e32 v76, v0
	v_mov_b32_e32 v77, v0
	v_mov_b32_e32 v78, v0
	v_mov_b32_e32 v79, v0
	v_mov_b32_e32 v84, v0
	v_mov_b32_e32 v85, v0
	v_mov_b32_e32 v86, v0
	v_mov_b32_e32 v87, v0
	v_mov_b32_e32 v92, v0
	v_mov_b32_e32 v93, v0
	v_mov_b32_e32 v94, v0
	v_mov_b32_e32 v95, v0
	v_mov_b32_e32 v100, v0
	v_mov_b32_e32 v101, v0
	v_mov_b32_e32 v102, v0
	v_mov_b32_e32 v103, v0
	v_mov_b32_e32 v108, v0
	v_mov_b32_e32 v109, v0
	v_mov_b32_e32 v110, v0
	v_mov_b32_e32 v111, v0
	v_mov_b32_e32 v116, v0
	v_mov_b32_e32 v117, v0
	v_mov_b32_e32 v118, v0
	v_mov_b32_e32 v119, v0
	v_mov_b32_e32 v124, v0
	v_mov_b32_e32 v125, v0
	v_mov_b32_e32 v126, v0
	v_mov_b32_e32 v127, v0
	v_mov_b32_e32 v64, v0
	v_mov_b32_e32 v65, v0
	v_mov_b32_e32 v66, v0
	v_mov_b32_e32 v67, v0
	v_mov_b32_e32 v72, v0
	v_mov_b32_e32 v73, v0
	v_mov_b32_e32 v74, v0
	v_mov_b32_e32 v75, v0
	v_mov_b32_e32 v80, v0
	v_mov_b32_e32 v81, v0
	v_mov_b32_e32 v82, v0
	v_mov_b32_e32 v83, v0
	v_mov_b32_e32 v88, v0
	v_mov_b32_e32 v89, v0
	v_mov_b32_e32 v90, v0
	v_mov_b32_e32 v91, v0
	v_mov_b32_e32 v96, v0
	v_mov_b32_e32 v97, v0
	v_mov_b32_e32 v98, v0
	v_mov_b32_e32 v99, v0
	v_mov_b32_e32 v104, v0
	v_mov_b32_e32 v105, v0
	v_mov_b32_e32 v106, v0
	v_mov_b32_e32 v107, v0
	v_mov_b32_e32 v112, v0
	v_mov_b32_e32 v113, v0
	v_mov_b32_e32 v114, v0
	v_mov_b32_e32 v115, v0
	v_mov_b32_e32 v120, v0
	v_mov_b32_e32 v121, v0
	v_mov_b32_e32 v122, v0
	v_mov_b32_e32 v123, v0

; __device__ __forceinline__ void load_rstd(float (&rsv)[2][4], const ssq_t* ssq, int row0) {
;     ssq_t t[2][4];
; #pragma unroll
;     for (int ai = 0; ai < 2; ++ai)
; #pragma unroll
;         for (int m = 0; m < 4; ++m) t[ai][m] = ssq[row0 + ai * HALF + m * 16];
; #pragma unroll
;     for (int ai = 0; ai < 2; ++ai)
; #pragma unroll
;         for (int m = 0; m < 4; ++m) rsv[ai][m] = __builtin_amdgcn_rsqf((float)t[ai][m] * (SSQ_INV / 1024.0f) + 1e-6f);
; }
;     __device__ __forceinline__ void operator()(const f32x4 (&acc)[2][2][4][2], const Unit& u, int wr, int wc, int fr, int fq) const {
;         const int row0 = u.pm * BM + wr * 64 + fr, col0 = u.pn * HALF + wc * 32 + 8 * fq;
;         float rsv[2][4]; load_rstd(rsv, ssq, row0);
.LBB0_311:
	v_lshrrev_b32_e32 v150, 8, v170
	v_and_b32_e32 v152, 15, v170
	v_lshl_add_u32 v150, v150, 6, v152
	s_lshl_b32 s10, s64, 8
	v_add_u32_e32 v150, s10, v150
	v_bfe_u32 v152, v170, 6, 2
	v_bfe_u32 v160, v170, 4, 2
	v_lshlrev_b32_e32 v152, 5, v152
	v_lshl_or_b32 v152, v160, 3, v152
	s_lshl_b32 s10, s63, 7
	v_add_u32_e32 v152, s10, v152
	v_mul_lo_u32 v160, v150, s28
	v_add_lshl_u32 v160, v160, v152, 1
	v_lshlrev_b32_e32 v166, 3, v150
	v_mov_b32_e32 v167, 0
	v_lshl_add_u64 v[166:167], v[166:167], 0, s[26:27]
	global_load_dwordx2 v[144:145], v[166:167], off
	global_load_dwordx2 v[146:147], v[166:167], off offset:128
	global_load_dwordx2 v[148:149], v[166:167], off offset:256
	global_load_dwordx2 v[154:155], v[166:167], off offset:384
	global_load_dwordx2 v[156:157], v[166:167], off offset:1024
	global_load_dwordx2 v[158:159], v[166:167], off offset:1152
	global_load_dwordx2 v[162:163], v[166:167], off offset:1280
	global_load_dwordx2 v[164:165], v[166:167], off offset:1408
	s_waitcnt vmcnt(0)
	v_ffbh_u32_e32 v150, v145
	v_min_u32_e32 v150, 32, v150
	v_lshlrev_b64 v[144:145], v150, v[144:145]
	v_min_u32_e32 v144, 1, v144
	v_or_b32_e32 v144, v145, v144
	v_cvt_f32_u32_e32 v144, v144
	v_sub_u32_e32 v150, 32, v150
	v_ldexp_f32 v144, v144, v150
	v_fmamk_f32 v144, v144, 0x30800000, v223
	v_rsq_f32_e32 v144, v144
	v_ffbh_u32_e32 v150, v147
	v_min_u32_e32 v150, 32, v150
	v_lshlrev_b64 v[146:147], v150, v[146:147]
	v_min_u32_e32 v146, 1, v146
	v_or_b32_e32 v146, v147, v146
	v_cvt_f32_u32_e32 v146, v146
	v_sub_u32_e32 v150, 32, v150
	v_ldexp_f32 v146, v146, v150
	v_fmamk_f32 v146, v146, 0x30800000, v223
	v_rsq_f32_e32 v146, v146
	v_ffbh_u32_e32 v150, v149
	v_min_u32_e32 v150, 32, v150
	v_lshlrev_b64 v[148:149], v150, v[148:149]
	v_min_u32_e32 v148, 1, v148
	v_or_b32_e32 v148, v149, v148
	v_cvt_f32_u32_e32 v148, v148
	v_sub_u32_e32 v150, 32, v150
	v_ldexp_f32 v148, v148, v150
	v_fmamk_f32 v148, v148, 0x30800000, v223
	v_rsq_f32_e32 v148, v148
	v_ffbh_u32_e32 v150, v155
	v_min_u32_e32 v150, 32, v150
	v_lshlrev_b64 v[154:155], v150, v[154:155]
	v_min_u32_e32 v154, 1, v154
	v_or_b32_e32 v154, v155, v154
	v_cvt_f32_u32_e32 v154, v154
	v_sub_u32_e32 v150, 32, v150
	v_ldexp_f32 v154, v154, v150
	v_fmamk_f32 v154, v154, 0x30800000, v223
	v_rsq_f32_e32 v154, v154
	v_ffbh_u32_e32 v150, v157
	v_min_u32_e32 v150, 32, v150
	v_lshlrev_b64 v[156:157], v150, v[156:157]
	v_min_u32_e32 v156, 1, v156
	v_or_b32_e32 v156, v157, v156
	v_cvt_f32_u32_e32 v156, v156
	v_sub_u32_e32 v150, 32, v150
	v_ldexp_f32 v156, v156, v150
	v_fmamk_f32 v156, v156, 0x30800000, v223
	v_rsq_f32_e32 v156, v156
	v_ffbh_u32_e32 v150, v159
	v_min_u32_e32 v150, 32, v150
	v_lshlrev_b64 v[158:159], v150, v[158:159]
	v_min_u32_e32 v158, 1, v158
	v_or_b32_e32 v158, v159, v158
	v_cvt_f32_u32_e32 v158, v158
	v_sub_u32_e32 v150, 32, v150
	v_ldexp_f32 v158, v158, v150
	v_fmamk_f32 v158, v158, 0x30800000, v223
	v_rsq_f32_e32 v158, v158
	v_ffbh_u32_e32 v150, v163
	v_min_u32_e32 v150, 32, v150
	v_lshlrev_b64 v[162:163], v150, v[162:163]
	v_min_u32_e32 v162, 1, v162
	v_or_b32_e32 v162, v163, v162
	v_cvt_f32_u32_e32 v162, v162
	v_sub_u32_e32 v150, 32, v150
	v_ldexp_f32 v162, v162, v150
	v_fmamk_f32 v162, v162, 0x30800000, v223
	v_rsq_f32_e32 v162, v162
	v_ffbh_u32_e32 v150, v165
	v_min_u32_e32 v150, 32, v150
	v_lshlrev_b64 v[164:165], v150, v[164:165]
	v_min_u32_e32 v164, 1, v164
	v_or_b32_e32 v164, v165, v164
	v_cvt_f32_u32_e32 v164, v164
	v_sub_u32_e32 v150, 32, v150
	v_ldexp_f32 v164, v164, v150
	v_fmamk_f32 v164, v164, 0x30800000, v223
	v_rsq_f32_e32 v164, v164
	v_mov_b32_e32 v172, v144
	v_mov_b32_e32 v173, v146
	v_mov_b32_e32 v236, v148
	v_mov_b32_e32 v237, v154
	v_mov_b32_e32 v238, v156
	v_mov_b32_e32 v239, v158
	v_mov_b32_e32 v230, v162
	v_mov_b32_e32 v231, v164
	v_mov_b32_e32 v254, s64
